# SwiGLU GEMM tile end: s_waitcnt vmcnt(0) replaced by counted vmcnt(8), the epilogue stores stay in flight across the tile boundary
# speedup vs baseline: 1.0194x; 1.0014x over previous
; DI unsigned pk2(float a, float b) { f2_t v = {a, b}; bf2_t r = __builtin_convertvector(v, bf2_t); return __builtin_bit_cast(unsigned, r); }
; DI float silu_mul(float a, float b) { return a * b * __builtin_amdgcn_rcpf(1.f + __builtin_amdgcn_exp2f(a * -1.4426950408889634f)); }
;   DI void operator()(f32x4 (&acc)[2][2][4][2], int brow, int bcol, int wr, int wc, int fr, int fq, const int nai) const {
;     const int bi = brow < M_LAT ? (brow >> 11) : 8;
;     const float* swr = sw + bi * SW_LD + bcol + wc * 32 + fq * 4;
;     const float4 sa0 = ld4(swr), sa1 = ld4(swr + 16), sb0 = ld4(swr + 128), sb1 = ld4(swr + 144);
;     u16* ob = act + (size_t)(brow + wr * 64 + fr) * DFF + (bcol >> 1) + wc * 32;
; #pragma unroll
;     for (int ai = 0; ai < 2; ++ai)
;      if (ai < nai)
; #pragma unroll
;       for (int m = 0; m < 4; ++m) {
;         const float r = rl[ai * 128 + wr * 64 + m * 16 + fr];
;         u16* o_ = ob + (size_t)(ai * 128 + m * 16) * DFF;
;         u32x2 p0, p1;
;         {
;           const f32x4 a = acc[ai][0][m][0], b = acc[ai][1][m][0];
;           p0[0] = pk2(silu_mul(a[0] * r + sa0.x, b[0] * r + sb0.x), silu_mul(a[1] * r + sa0.y, b[1] * r + sb0.y));
;           p0[1] = pk2(silu_mul(a[2] * r + sa0.z, b[2] * r + sb0.z), silu_mul(a[3] * r + sa0.w, b[3] * r + sb0.w));
;         }
;         {
;           const f32x4 a = acc[ai][0][m][1], b = acc[ai][1][m][1];
;           p1[0] = pk2(silu_mul(a[0] * r + sa1.x, b[0] * r + sb1.x), silu_mul(a[1] * r + sa1.y, b[1] * r + sb1.y));
;           p1[1] = pk2(silu_mul(a[2] * r + sa1.z, b[2] * r + sb1.z), silu_mul(a[3] * r + sa1.w, b[3] * r + sb1.w));
;         }
;         store_nn16(o_, p0, p1, fq);
;       }
.LBB0_969:
	s_min_i32 s0, s2, 0x4000
	s_ashr_i32 s0, s0, 11
	s_mul_hi_i32 s1, s0, 0x5800
	s_mulk_i32 s0, 0x5800
	s_add_u32 s3, s16, s0
	s_addc_u32 s4, s17, s1
	s_lshl_b64 s[0:1], s[8:9], 2
	v_lshrrev_b32_e32 v33, 1, v138
	s_add_u32 s0, s3, s0
	v_and_b32_e32 v34, 0x60, v33
	s_addc_u32 s1, s4, s1
	v_lshlrev_b32_e32 v0, 2, v34
	v_lshl_add_u64 v[30:31], s[0:1], 0, v[0:1]
	v_and_b32_e32 v0, 48, v138
	v_and_b32_e32 v32, 15, v138
	v_lshl_add_u64 v[142:143], v[30:31], 0, v[0:1]
	v_ashrrev_i32_e32 v0, 2, v138
	v_and_b32_e32 v35, 0xffffffc0, v0
	v_or_b32_e32 v0, s2, v32
	v_add_u32_e32 v0, v0, v35
	v_mov_b64_e32 v[30:31], s[40:41]
	s_movk_i32 s0, 0x1600
	v_mad_i64_i32 v[30:31], s[0:1], v0, s0, v[30:31]
	s_lshl_b32 s0, s20, 7
	s_ashr_i32 s1, s0, 31
	v_lshl_add_u64 v[30:31], s[0:1], 1, v[30:31]
	v_lshlrev_b32_e32 v0, 1, v34
	v_lshl_add_u64 v[30:31], v[30:31], 0, v[0:1]
	v_and_b32_e32 v0, 16, v138
	v_lshlrev_b32_e32 v0, 1, v0
	v_lshl_add_u64 v[30:31], v[30:31], 0, v[0:1]
	v_and_b32_e32 v0, 16, v33
	v_lshl_add_u64 v[138:139], v[30:31], 0, v[0:1]
	s_add_i32 s0, 0, 0x25040
	v_lshlrev_b32_e32 v0, 2, v35
	v_lshlrev_b32_e32 v30, 2, v32
	v_add3_u32 v144, s0, v0, v30
	ds_read2_b32 v[140:141], v144 offset1:16
	s_mov_b32 s0, 0x16000
	s_waitcnt lgkmcnt(0)
	v_pk_fma_f32 v[42:43], v[42:43], v[140:141], v[160:161] op_sel_hi:[1,0,1]
	s_nop 0
	v_mul_f32_e32 v0, 0xbfb8aa3b, v42
	v_exp_f32_e32 v0, v0
	v_pk_fma_f32 v[46:47], v[46:47], v[140:141], v[164:165] op_sel_hi:[1,0,1]
	v_add_f32_e32 v0, 1.0, v0
	v_rcp_f32_e32 v146, v0
	v_mul_f32_e32 v0, 0xbfb8aa3b, v43
	v_exp_f32_e32 v0, v0
	v_pk_mul_f32 v[46:47], v[42:43], v[46:47]
	v_add_f32_e32 v0, 1.0, v0
	v_rcp_f32_e32 v147, v0
	s_nop 0
	v_pk_mul_f32 v[42:43], v[46:47], v[146:147]
	s_nop 0
	v_cvt_pk_bf16_f32 v146, v42, v43
	v_pk_fma_f32 v[42:43], v[44:45], v[140:141], v[162:163] op_sel_hi:[1,0,1]
	v_pk_fma_f32 v[46:47], v[48:49], v[140:141], v[166:167] op_sel_hi:[1,0,1]
	v_mul_f32_e32 v0, 0xbfb8aa3b, v42
	v_exp_f32_e32 v0, v0
	v_pk_mul_f32 v[46:47], v[42:43], v[46:47]
	v_add_f32_e32 v0, 1.0, v0
	v_rcp_f32_e32 v44, v0
	v_mul_f32_e32 v0, 0xbfb8aa3b, v43
	v_exp_f32_e32 v0, v0
	s_nop 0
	v_add_f32_e32 v0, 1.0, v0
	v_rcp_f32_e32 v45, v0
	s_nop 0
	v_pk_mul_f32 v[42:43], v[46:47], v[44:45]
	s_nop 0
	v_cvt_pk_bf16_f32 v147, v42, v43
	v_pk_fma_f32 v[130:131], v[130:131], v[140:141], v[168:169] op_sel_hi:[1,0,1]
	s_nop 0
	v_mul_f32_e32 v0, 0xbfb8aa3b, v130
	v_exp_f32_e32 v0, v0
	v_pk_fma_f32 v[134:135], v[134:135], v[140:141], v[172:173] op_sel_hi:[1,0,1]
	v_add_f32_e32 v0, 1.0, v0
	v_rcp_f32_e32 v142, v0
	v_mul_f32_e32 v0, 0xbfb8aa3b, v131
	v_exp_f32_e32 v0, v0
	v_pk_mul_f32 v[134:135], v[130:131], v[134:135]
	v_add_f32_e32 v0, 1.0, v0
	v_rcp_f32_e32 v143, v0
	s_nop 0
	v_pk_mul_f32 v[130:131], v[134:135], v[142:143]
	s_nop 0
	v_cvt_pk_bf16_f32 v148, v130, v131
	v_pk_fma_f32 v[130:131], v[132:133], v[140:141], v[170:171] op_sel_hi:[1,0,1]
	v_pk_fma_f32 v[134:135], v[136:137], v[140:141], v[174:175] op_sel_hi:[1,0,1]
	v_mul_f32_e32 v0, 0xbfb8aa3b, v130
	v_exp_f32_e32 v0, v0
	v_pk_mul_f32 v[134:135], v[130:131], v[134:135]
	v_permlane16_swap_b32_e32 v146, v148
	v_add_f32_e32 v0, 1.0, v0
	v_rcp_f32_e32 v132, v0
	v_mul_f32_e32 v0, 0xbfb8aa3b, v131
	v_exp_f32_e32 v0, v0
	s_nop 0
	v_add_f32_e32 v0, 1.0, v0
	v_rcp_f32_e32 v133, v0
	v_mov_b32_e32 v0, v141
	v_pk_fma_f32 v[122:123], v[122:123], v[0:1], v[160:161] op_sel_hi:[1,0,1]
	v_pk_fma_f32 v[126:127], v[126:127], v[0:1], v[164:165] op_sel_hi:[1,0,1]
	v_pk_mul_f32 v[130:131], v[134:135], v[132:133]
	v_pk_mul_f32 v[126:127], v[122:123], v[126:127]
	v_cvt_pk_bf16_f32 v149, v130, v131
	v_mul_f32_e32 v130, 0xbfb8aa3b, v122
	v_mul_f32_e32 v122, 0xbfb8aa3b, v123
	v_exp_f32_e32 v130, v130
	v_exp_f32_e32 v122, v122
	v_pk_fma_f32 v[124:125], v[124:125], v[0:1], v[162:163] op_sel_hi:[1,0,1]
	v_pk_fma_f32 v[128:129], v[128:129], v[0:1], v[166:167] op_sel_hi:[1,0,1]
	v_add_f32_e32 v130, 1.0, v130
	v_add_f32_e32 v122, 1.0, v122
	v_rcp_f32_e32 v130, v130
	v_rcp_f32_e32 v131, v122
	v_pk_mul_f32 v[128:129], v[124:125], v[128:129]
	v_pk_fma_f32 v[114:115], v[114:115], v[0:1], v[168:169] op_sel_hi:[1,0,1]
	v_pk_fma_f32 v[118:119], v[118:119], v[0:1], v[172:173] op_sel_hi:[1,0,1]
	v_pk_mul_f32 v[122:123], v[126:127], v[130:131]
	v_pk_mul_f32 v[118:119], v[114:115], v[118:119]
	v_cvt_pk_bf16_f32 v122, v122, v123
	v_mul_f32_e32 v123, 0xbfb8aa3b, v124
	v_exp_f32_e32 v123, v123
	v_permlane16_swap_b32_e32 v147, v149
	global_store_dwordx4 v[138:139], v[146:149], off
	v_add_f32_e32 v123, 1.0, v123
	v_rcp_f32_e32 v126, v123
	v_mul_f32_e32 v123, 0xbfb8aa3b, v125
	v_exp_f32_e32 v123, v123
	s_nop 0
	v_add_f32_e32 v123, 1.0, v123
	v_rcp_f32_e32 v127, v123
	s_nop 0
	v_pk_mul_f32 v[124:125], v[128:129], v[126:127]
	s_nop 0
	v_cvt_pk_bf16_f32 v123, v124, v125
	v_mul_f32_e32 v124, 0xbfb8aa3b, v114
	v_mul_f32_e32 v114, 0xbfb8aa3b, v115
	v_exp_f32_e32 v124, v124
	v_exp_f32_e32 v114, v114
	v_add_f32_e32 v124, 1.0, v124
	v_add_f32_e32 v114, 1.0, v114
	v_rcp_f32_e32 v124, v124
	v_rcp_f32_e32 v125, v114
	s_nop 0
	v_pk_mul_f32 v[114:115], v[118:119], v[124:125]
	s_nop 0
	v_cvt_pk_bf16_f32 v124, v114, v115
	v_pk_fma_f32 v[114:115], v[116:117], v[0:1], v[170:171] op_sel_hi:[1,0,1]
	v_pk_fma_f32 v[118:119], v[120:121], v[0:1], v[174:175] op_sel_hi:[1,0,1]
	v_mul_f32_e32 v116, 0xbfb8aa3b, v114
	v_mul_f32_e32 v0, 0xbfb8aa3b, v115
	v_exp_f32_e32 v116, v116
	v_exp_f32_e32 v0, v0
	v_pk_mul_f32 v[118:119], v[114:115], v[118:119]
	v_permlane16_swap_b32_e32 v122, v124
	v_add_f32_e32 v116, 1.0, v116
	v_add_f32_e32 v0, 1.0, v0
	v_rcp_f32_e32 v116, v116
	v_rcp_f32_e32 v117, v0
	s_nop 0
	v_pk_mul_f32 v[114:115], v[118:119], v[116:117]
	s_nop 0
	v_cvt_pk_bf16_f32 v125, v114, v115
	v_add_co_u32_e32 v114, vcc, s0, v138
	s_nop 0
	v_permlane16_swap_b32_e32 v123, v125
	v_addc_co_u32_e32 v115, vcc, 0, v139, vcc
	global_store_dwordx4 v[114:115], v[122:125], off
	ds_read2_b32 v[114:115], v144 offset0:32 offset1:48
	s_mov_b32 s0, 0x2c000
	s_waitcnt lgkmcnt(0)
; DI unsigned pk2(float a, float b) { f2_t v = {a, b}; bf2_t r = __builtin_convertvector(v, bf2_t); return __builtin_bit_cast(unsigned, r); }
; DI float silu_mul(float a, float b) { return a * b * __builtin_amdgcn_rcpf(1.f + __builtin_amdgcn_exp2f(a * -1.4426950408889634f)); }
;   DI void operator()(f32x4 (&acc)[2][2][4][2], int brow, int bcol, int wr, int wc, int fr, int fq, const int nai) const {
;     ...
;         const float r = rl[ai * 128 + wr * 64 + m * 16 + fr];
;         u16* o_ = ob + (size_t)(ai * 128 + m * 16) * DFF;
;         u32x2 p0, p1;
;         {
;           const f32x4 a = acc[ai][0][m][0], b = acc[ai][1][m][0];
;           p0[0] = pk2(silu_mul(a[0] * r + sa0.x, b[0] * r + sb0.x), silu_mul(a[1] * r + sa0.y, b[1] * r + sb0.y));
;           p0[1] = pk2(silu_mul(a[2] * r + sa0.z, b[2] * r + sb0.z), silu_mul(a[3] * r + sa0.w, b[3] * r + sb0.w));
;         }
;         {
;           const f32x4 a = acc[ai][0][m][1], b = acc[ai][1][m][1];
;           p1[0] = pk2(silu_mul(a[0] * r + sa1.x, b[0] * r + sb1.x), silu_mul(a[1] * r + sa1.y, b[1] * r + sb1.y));
;           p1[1] = pk2(silu_mul(a[2] * r + sa1.z, b[2] * r + sb1.z), silu_mul(a[3] * r + sa1.w, b[3] * r + sb1.w));
;         }
;         store_nn16(o_, p0, p1, fq);
;       }
	v_pk_fma_f32 v[106:107], v[106:107], v[114:115], v[160:161] op_sel_hi:[1,0,1]
	s_nop 0
	v_mul_f32_e32 v0, 0xbfb8aa3b, v106
	v_exp_f32_e32 v0, v0
	v_pk_fma_f32 v[108:109], v[108:109], v[114:115], v[162:163] op_sel_hi:[1,0,1]
	v_pk_fma_f32 v[110:111], v[110:111], v[114:115], v[164:165] op_sel_hi:[1,0,1]
	v_pk_fma_f32 v[98:99], v[98:99], v[114:115], v[168:169] op_sel_hi:[1,0,1]
	v_add_f32_e32 v0, 1.0, v0
	v_rcp_f32_e32 v116, v0
	v_mul_f32_e32 v0, 0xbfb8aa3b, v107
	v_exp_f32_e32 v0, v0
	v_pk_mul_f32 v[110:111], v[106:107], v[110:111]
	v_pk_fma_f32 v[112:113], v[112:113], v[114:115], v[166:167] op_sel_hi:[1,0,1]
	v_pk_fma_f32 v[102:103], v[102:103], v[114:115], v[172:173] op_sel_hi:[1,0,1]
	v_add_f32_e32 v0, 1.0, v0
	v_rcp_f32_e32 v117, v0
	v_mul_f32_e32 v0, 0xbfb8aa3b, v108
	v_exp_f32_e32 v0, v0
	v_pk_mul_f32 v[112:113], v[108:109], v[112:113]
	v_pk_mul_f32 v[106:107], v[110:111], v[116:117]
	v_pk_mul_f32 v[102:103], v[98:99], v[102:103]
	v_add_f32_e32 v0, 1.0, v0
	v_rcp_f32_e32 v110, v0
	v_mul_f32_e32 v0, 0xbfb8aa3b, v109
	v_exp_f32_e32 v0, v0
	v_cvt_pk_bf16_f32 v106, v106, v107
	v_add_f32_e32 v0, 1.0, v0
	v_rcp_f32_e32 v111, v0
	v_mul_f32_e32 v0, 0xbfb8aa3b, v98
	v_exp_f32_e32 v0, v0
	v_pk_mul_f32 v[108:109], v[112:113], v[110:111]
	s_nop 0
	v_cvt_pk_bf16_f32 v107, v108, v109
	v_add_f32_e32 v0, 1.0, v0
	v_rcp_f32_e32 v108, v0
	v_mul_f32_e32 v0, 0xbfb8aa3b, v99
	v_exp_f32_e32 v0, v0
	s_nop 0
	v_add_f32_e32 v0, 1.0, v0
	v_rcp_f32_e32 v109, v0
	s_nop 0
	v_pk_mul_f32 v[98:99], v[102:103], v[108:109]
	s_nop 0
	v_cvt_pk_bf16_f32 v108, v98, v99
	v_pk_fma_f32 v[98:99], v[100:101], v[114:115], v[170:171] op_sel_hi:[1,0,1]
	v_pk_fma_f32 v[102:103], v[104:105], v[114:115], v[174:175] op_sel_hi:[1,0,1]
	v_mul_f32_e32 v0, 0xbfb8aa3b, v98
	v_exp_f32_e32 v0, v0
	v_pk_mul_f32 v[102:103], v[98:99], v[102:103]
	v_permlane16_swap_b32_e32 v106, v108
	v_add_f32_e32 v0, 1.0, v0
	v_rcp_f32_e32 v100, v0
	v_mul_f32_e32 v0, 0xbfb8aa3b, v99
	v_exp_f32_e32 v0, v0
	s_nop 0
	v_add_f32_e32 v0, 1.0, v0
	v_rcp_f32_e32 v101, v0
	v_mov_b32_e32 v0, v115
	v_pk_fma_f32 v[90:91], v[90:91], v[0:1], v[160:161] op_sel_hi:[1,0,1]
	v_pk_fma_f32 v[94:95], v[94:95], v[0:1], v[164:165] op_sel_hi:[1,0,1]
	v_pk_mul_f32 v[98:99], v[102:103], v[100:101]
	v_pk_mul_f32 v[94:95], v[90:91], v[94:95]
	v_cvt_pk_bf16_f32 v109, v98, v99
	v_add_co_u32_e32 v98, vcc, s0, v138
	s_nop 0
	v_permlane16_swap_b32_e32 v107, v109
	v_addc_co_u32_e32 v99, vcc, 0, v139, vcc
	global_store_dwordx4 v[98:99], v[106:109], off
	v_mul_f32_e32 v98, 0xbfb8aa3b, v90
	v_mul_f32_e32 v90, 0xbfb8aa3b, v91
	v_exp_f32_e32 v98, v98
	v_exp_f32_e32 v90, v90
	v_pk_fma_f32 v[92:93], v[92:93], v[0:1], v[162:163] op_sel_hi:[1,0,1]
	v_pk_fma_f32 v[96:97], v[96:97], v[0:1], v[166:167] op_sel_hi:[1,0,1]
	v_add_f32_e32 v98, 1.0, v98
	v_add_f32_e32 v90, 1.0, v90
	v_rcp_f32_e32 v98, v98
	v_rcp_f32_e32 v99, v90
	v_pk_mul_f32 v[96:97], v[92:93], v[96:97]
	v_pk_fma_f32 v[82:83], v[82:83], v[0:1], v[168:169] op_sel_hi:[1,0,1]
	v_pk_fma_f32 v[86:87], v[86:87], v[0:1], v[172:173] op_sel_hi:[1,0,1]
	v_pk_mul_f32 v[90:91], v[94:95], v[98:99]
	v_pk_mul_f32 v[86:87], v[82:83], v[86:87]
	v_cvt_pk_bf16_f32 v90, v90, v91
	v_mul_f32_e32 v91, 0xbfb8aa3b, v92
	v_exp_f32_e32 v91, v91
	s_mov_b32 s0, 0x42000
	v_add_f32_e32 v91, 1.0, v91
	v_rcp_f32_e32 v94, v91
	v_mul_f32_e32 v91, 0xbfb8aa3b, v93
	v_exp_f32_e32 v91, v91
	s_nop 0
	v_add_f32_e32 v91, 1.0, v91
	v_rcp_f32_e32 v95, v91
	s_nop 0
	v_pk_mul_f32 v[92:93], v[96:97], v[94:95]
	s_nop 0
	v_cvt_pk_bf16_f32 v91, v92, v93
	v_mul_f32_e32 v92, 0xbfb8aa3b, v82
	v_mul_f32_e32 v82, 0xbfb8aa3b, v83
	v_exp_f32_e32 v92, v92
	v_exp_f32_e32 v82, v82
	v_add_f32_e32 v92, 1.0, v92
	v_add_f32_e32 v82, 1.0, v82
	v_rcp_f32_e32 v92, v92
	v_rcp_f32_e32 v93, v82
	s_nop 0
	v_pk_mul_f32 v[82:83], v[86:87], v[92:93]
	s_nop 0
	v_cvt_pk_bf16_f32 v92, v82, v83
	v_pk_fma_f32 v[82:83], v[84:85], v[0:1], v[170:171] op_sel_hi:[1,0,1]
	v_pk_fma_f32 v[86:87], v[88:89], v[0:1], v[174:175] op_sel_hi:[1,0,1]
	v_mul_f32_e32 v84, 0xbfb8aa3b, v82
	v_mul_f32_e32 v0, 0xbfb8aa3b, v83
	v_exp_f32_e32 v84, v84
	v_exp_f32_e32 v0, v0
	v_pk_mul_f32 v[86:87], v[82:83], v[86:87]
	v_permlane16_swap_b32_e32 v90, v92
	v_add_f32_e32 v84, 1.0, v84
	v_add_f32_e32 v0, 1.0, v0
	v_rcp_f32_e32 v84, v84
	v_rcp_f32_e32 v85, v0
	s_nop 0
	v_pk_mul_f32 v[82:83], v[86:87], v[84:85]
	s_nop 0
	v_cvt_pk_bf16_f32 v93, v82, v83
	v_add_co_u32_e32 v82, vcc, s0, v138
	s_nop 0
	v_permlane16_swap_b32_e32 v91, v93
	v_addc_co_u32_e32 v83, vcc, 0, v139, vcc
	global_store_dwordx4 v[82:83], v[90:93], off
	ds_read2_b32 v[82:83], v144 offset0:128 offset1:144
	s_mov_b32 s0, 0xb0000
	s_waitcnt lgkmcnt(0)
; DI unsigned pk2(float a, float b) { f2_t v = {a, b}; bf2_t r = __builtin_convertvector(v, bf2_t); return __builtin_bit_cast(unsigned, r); }
; DI float silu_mul(float a, float b) { return a * b * __builtin_amdgcn_rcpf(1.f + __builtin_amdgcn_exp2f(a * -1.4426950408889634f)); }
;   DI void operator()(f32x4 (&acc)[2][2][4][2], int brow, int bcol, int wr, int wc, int fr, int fq, const int nai) const {
;     ...
;         const float r = rl[ai * 128 + wr * 64 + m * 16 + fr];
;         u16* o_ = ob + (size_t)(ai * 128 + m * 16) * DFF;
;         u32x2 p0, p1;
;         {
;           const f32x4 a = acc[ai][0][m][0], b = acc[ai][1][m][0];
;           p0[0] = pk2(silu_mul(a[0] * r + sa0.x, b[0] * r + sb0.x), silu_mul(a[1] * r + sa0.y, b[1] * r + sb0.y));
;           p0[1] = pk2(silu_mul(a[2] * r + sa0.z, b[2] * r + sb0.z), silu_mul(a[3] * r + sa0.w, b[3] * r + sb0.w));
;         }
;         {
;           const f32x4 a = acc[ai][0][m][1], b = acc[ai][1][m][1];
;           p1[0] = pk2(silu_mul(a[0] * r + sa1.x, b[0] * r + sb1.x), silu_mul(a[1] * r + sa1.y, b[1] * r + sb1.y));
;           p1[1] = pk2(silu_mul(a[2] * r + sa1.z, b[2] * r + sb1.z), silu_mul(a[3] * r + sa1.w, b[3] * r + sb1.w));
;         }
;         store_nn16(o_, p0, p1, fq);
;       }
	v_pk_fma_f32 v[74:75], v[74:75], v[82:83], v[160:161] op_sel_hi:[1,0,1]
	s_nop 0
	v_mul_f32_e32 v0, 0xbfb8aa3b, v74
	v_exp_f32_e32 v0, v0
	v_pk_fma_f32 v[76:77], v[76:77], v[82:83], v[162:163] op_sel_hi:[1,0,1]
	v_pk_fma_f32 v[78:79], v[78:79], v[82:83], v[164:165] op_sel_hi:[1,0,1]
	v_pk_fma_f32 v[66:67], v[66:67], v[82:83], v[168:169] op_sel_hi:[1,0,1]
	v_add_f32_e32 v0, 1.0, v0
	v_rcp_f32_e32 v84, v0
	v_mul_f32_e32 v0, 0xbfb8aa3b, v75
	v_exp_f32_e32 v0, v0
	v_pk_mul_f32 v[78:79], v[74:75], v[78:79]
	v_pk_fma_f32 v[80:81], v[80:81], v[82:83], v[166:167] op_sel_hi:[1,0,1]
	v_pk_fma_f32 v[70:71], v[70:71], v[82:83], v[172:173] op_sel_hi:[1,0,1]
	v_add_f32_e32 v0, 1.0, v0
	v_rcp_f32_e32 v85, v0
	v_mul_f32_e32 v0, 0xbfb8aa3b, v76
	v_exp_f32_e32 v0, v0
	v_pk_mul_f32 v[80:81], v[76:77], v[80:81]
	v_pk_mul_f32 v[74:75], v[78:79], v[84:85]
	v_pk_mul_f32 v[70:71], v[66:67], v[70:71]
	v_add_f32_e32 v0, 1.0, v0
	v_rcp_f32_e32 v78, v0
	v_mul_f32_e32 v0, 0xbfb8aa3b, v77
	v_exp_f32_e32 v0, v0
	v_cvt_pk_bf16_f32 v74, v74, v75
	v_add_f32_e32 v0, 1.0, v0
	v_rcp_f32_e32 v79, v0
	v_mul_f32_e32 v0, 0xbfb8aa3b, v66
	v_exp_f32_e32 v0, v0
	v_pk_mul_f32 v[76:77], v[80:81], v[78:79]
	s_nop 0
	v_cvt_pk_bf16_f32 v75, v76, v77
	v_add_f32_e32 v0, 1.0, v0
	v_rcp_f32_e32 v76, v0
	v_mul_f32_e32 v0, 0xbfb8aa3b, v67
	v_exp_f32_e32 v0, v0
	s_nop 0
	v_add_f32_e32 v0, 1.0, v0
	v_rcp_f32_e32 v77, v0
	s_nop 0
	v_pk_mul_f32 v[66:67], v[70:71], v[76:77]
	s_nop 0
	v_cvt_pk_bf16_f32 v76, v66, v67
	v_pk_fma_f32 v[66:67], v[68:69], v[82:83], v[170:171] op_sel_hi:[1,0,1]
	v_pk_fma_f32 v[70:71], v[72:73], v[82:83], v[174:175] op_sel_hi:[1,0,1]
	v_mul_f32_e32 v0, 0xbfb8aa3b, v66
	v_exp_f32_e32 v0, v0
	v_pk_mul_f32 v[70:71], v[66:67], v[70:71]
	v_permlane16_swap_b32_e32 v74, v76
	v_add_f32_e32 v0, 1.0, v0
	v_rcp_f32_e32 v68, v0
	v_mul_f32_e32 v0, 0xbfb8aa3b, v67
	v_exp_f32_e32 v0, v0
	s_nop 0
	v_add_f32_e32 v0, 1.0, v0
	v_rcp_f32_e32 v69, v0
	v_mov_b32_e32 v0, v83
	v_pk_fma_f32 v[58:59], v[58:59], v[0:1], v[160:161] op_sel_hi:[1,0,1]
	v_pk_fma_f32 v[62:63], v[62:63], v[0:1], v[164:165] op_sel_hi:[1,0,1]
	v_pk_mul_f32 v[66:67], v[70:71], v[68:69]
	v_pk_mul_f32 v[62:63], v[58:59], v[62:63]
	v_cvt_pk_bf16_f32 v77, v66, v67
	v_add_co_u32_e32 v66, vcc, s0, v138
	s_nop 0
	v_permlane16_swap_b32_e32 v75, v77
	v_addc_co_u32_e32 v67, vcc, 0, v139, vcc
	global_store_dwordx4 v[66:67], v[74:77], off
	v_mul_f32_e32 v66, 0xbfb8aa3b, v58
	v_mul_f32_e32 v58, 0xbfb8aa3b, v59
	v_exp_f32_e32 v66, v66
	v_exp_f32_e32 v58, v58
	v_pk_fma_f32 v[60:61], v[60:61], v[0:1], v[162:163] op_sel_hi:[1,0,1]
	v_pk_fma_f32 v[64:65], v[64:65], v[0:1], v[166:167] op_sel_hi:[1,0,1]
	v_add_f32_e32 v66, 1.0, v66
	v_add_f32_e32 v58, 1.0, v58
	v_rcp_f32_e32 v66, v66
	v_rcp_f32_e32 v67, v58
	v_pk_mul_f32 v[64:65], v[60:61], v[64:65]
	v_pk_fma_f32 v[50:51], v[50:51], v[0:1], v[168:169] op_sel_hi:[1,0,1]
	v_pk_fma_f32 v[54:55], v[54:55], v[0:1], v[172:173] op_sel_hi:[1,0,1]
	v_pk_mul_f32 v[58:59], v[62:63], v[66:67]
	v_pk_mul_f32 v[54:55], v[50:51], v[54:55]
	v_cvt_pk_bf16_f32 v58, v58, v59
	v_mul_f32_e32 v59, 0xbfb8aa3b, v60
	v_exp_f32_e32 v59, v59
	s_mov_b32 s0, 0xc6000
	v_add_f32_e32 v59, 1.0, v59
	v_rcp_f32_e32 v62, v59
	v_mul_f32_e32 v59, 0xbfb8aa3b, v61
	v_exp_f32_e32 v59, v59
	s_nop 0
	v_add_f32_e32 v59, 1.0, v59
	v_rcp_f32_e32 v63, v59
	s_nop 0
	v_pk_mul_f32 v[60:61], v[64:65], v[62:63]
	s_nop 0
	v_cvt_pk_bf16_f32 v59, v60, v61
	v_mul_f32_e32 v60, 0xbfb8aa3b, v50
	v_mul_f32_e32 v50, 0xbfb8aa3b, v51
	v_exp_f32_e32 v60, v60
	v_exp_f32_e32 v50, v50
	v_add_f32_e32 v60, 1.0, v60
	v_add_f32_e32 v50, 1.0, v50
	v_rcp_f32_e32 v60, v60
	v_rcp_f32_e32 v61, v50
	s_nop 0
	v_pk_mul_f32 v[50:51], v[54:55], v[60:61]
	s_nop 0
	v_cvt_pk_bf16_f32 v60, v50, v51
	v_pk_fma_f32 v[50:51], v[52:53], v[0:1], v[170:171] op_sel_hi:[1,0,1]
	v_pk_fma_f32 v[54:55], v[56:57], v[0:1], v[174:175] op_sel_hi:[1,0,1]
	v_mul_f32_e32 v52, 0xbfb8aa3b, v50
	v_mul_f32_e32 v0, 0xbfb8aa3b, v51
	v_exp_f32_e32 v52, v52
	v_exp_f32_e32 v0, v0
	v_pk_mul_f32 v[54:55], v[50:51], v[54:55]
	v_permlane16_swap_b32_e32 v58, v60
	v_add_f32_e32 v52, 1.0, v52
	v_add_f32_e32 v0, 1.0, v0
	v_rcp_f32_e32 v52, v52
	v_rcp_f32_e32 v53, v0
	s_nop 0
	v_pk_mul_f32 v[50:51], v[54:55], v[52:53]
	s_nop 0
	v_cvt_pk_bf16_f32 v61, v50, v51
	v_add_co_u32_e32 v50, vcc, s0, v138
	s_nop 0
	v_permlane16_swap_b32_e32 v59, v61
	v_addc_co_u32_e32 v51, vcc, 0, v139, vcc
	global_store_dwordx4 v[50:51], v[58:61], off
	ds_read2_b32 v[50:51], v144 offset0:160 offset1:176
	s_mov_b32 s0, 0xdc000
	s_waitcnt lgkmcnt(0)
; DI unsigned pk2(float a, float b) { f2_t v = {a, b}; bf2_t r = __builtin_convertvector(v, bf2_t); return __builtin_bit_cast(unsigned, r); }
; #define WAIT_V(n) asm volatile("s_waitcnt vmcnt(" #n ")" ::: "memory")
; DI float silu_mul(float a, float b) { return a * b * __builtin_amdgcn_rcpf(1.f + __builtin_amdgcn_exp2f(a * -1.4426950408889634f)); }
; template <int K, bool HALFM, class Epi>
; DI void gemm_tile(unsigned char* lds, const int tid, const u16* __restrict__ A, const u16* __restrict__ Bt, int brow, int bcol, Epi& epi,
;                   const bool prefetched, const bool has_next, const int nbrow, const int nbcol) {
;     ...
;   WAIT_V(0);
;   DI void operator()(f32x4 (&acc)[2][2][4][2], int brow, int bcol, int wr, int wc, int fr, int fq, const int nai) const {
;     ...
;         const float r = rl[ai * 128 + wr * 64 + m * 16 + fr];
;         u16* o_ = ob + (size_t)(ai * 128 + m * 16) * DFF;
;         u32x2 p0, p1;
;         {
;           const f32x4 a = acc[ai][0][m][0], b = acc[ai][1][m][0];
;           p0[0] = pk2(silu_mul(a[0] * r + sa0.x, b[0] * r + sb0.x), silu_mul(a[1] * r + sa0.y, b[1] * r + sb0.y));
;           p0[1] = pk2(silu_mul(a[2] * r + sa0.z, b[2] * r + sb0.z), silu_mul(a[3] * r + sa0.w, b[3] * r + sb0.w));
;         }
;         {
;           const f32x4 a = acc[ai][0][m][1], b = acc[ai][1][m][1];
;           p1[0] = pk2(silu_mul(a[0] * r + sa1.x, b[0] * r + sb1.x), silu_mul(a[1] * r + sa1.y, b[1] * r + sb1.y));
;           p1[1] = pk2(silu_mul(a[2] * r + sa1.z, b[2] * r + sb1.z), silu_mul(a[3] * r + sa1.w, b[3] * r + sb1.w));
;         }
;         store_nn16(o_, p0, p1, fq);
;       }
	v_pk_fma_f32 v[26:27], v[26:27], v[50:51], v[160:161] op_sel_hi:[1,0,1]
	s_nop 0
	v_mul_f32_e32 v0, 0xbfb8aa3b, v26
	v_exp_f32_e32 v0, v0
	v_pk_fma_f32 v[28:29], v[28:29], v[50:51], v[162:163] op_sel_hi:[1,0,1]
	v_pk_fma_f32 v[38:39], v[38:39], v[50:51], v[164:165] op_sel_hi:[1,0,1]
	v_pk_fma_f32 v[18:19], v[18:19], v[50:51], v[168:169] op_sel_hi:[1,0,1]
	v_add_f32_e32 v0, 1.0, v0
	v_rcp_f32_e32 v52, v0
	v_mul_f32_e32 v0, 0xbfb8aa3b, v27
	v_exp_f32_e32 v0, v0
	v_pk_mul_f32 v[38:39], v[26:27], v[38:39]
	v_pk_fma_f32 v[40:41], v[40:41], v[50:51], v[166:167] op_sel_hi:[1,0,1]
	v_pk_fma_f32 v[22:23], v[22:23], v[50:51], v[172:173] op_sel_hi:[1,0,1]
	v_add_f32_e32 v0, 1.0, v0
	v_rcp_f32_e32 v53, v0
	v_mul_f32_e32 v0, 0xbfb8aa3b, v28
	v_exp_f32_e32 v0, v0
	v_pk_mul_f32 v[40:41], v[28:29], v[40:41]
	v_pk_mul_f32 v[26:27], v[38:39], v[52:53]
	v_pk_mul_f32 v[22:23], v[18:19], v[22:23]
	v_add_f32_e32 v0, 1.0, v0
	v_rcp_f32_e32 v38, v0
	v_mul_f32_e32 v0, 0xbfb8aa3b, v29
	v_exp_f32_e32 v0, v0
	v_cvt_pk_bf16_f32 v26, v26, v27
	v_add_f32_e32 v0, 1.0, v0
	v_rcp_f32_e32 v39, v0
	v_mul_f32_e32 v0, 0xbfb8aa3b, v18
	v_exp_f32_e32 v0, v0
	v_pk_mul_f32 v[28:29], v[40:41], v[38:39]
	s_nop 0
	v_cvt_pk_bf16_f32 v27, v28, v29
	v_add_f32_e32 v0, 1.0, v0
	v_rcp_f32_e32 v28, v0
	v_mul_f32_e32 v0, 0xbfb8aa3b, v19
	v_exp_f32_e32 v0, v0
	s_nop 0
	v_add_f32_e32 v0, 1.0, v0
	v_rcp_f32_e32 v29, v0
	s_nop 0
	v_pk_mul_f32 v[18:19], v[22:23], v[28:29]
	s_nop 0
	v_cvt_pk_bf16_f32 v28, v18, v19
	v_pk_fma_f32 v[18:19], v[20:21], v[50:51], v[170:171] op_sel_hi:[1,0,1]
	v_pk_fma_f32 v[22:23], v[24:25], v[50:51], v[174:175] op_sel_hi:[1,0,1]
	v_mul_f32_e32 v0, 0xbfb8aa3b, v18
	v_exp_f32_e32 v0, v0
	v_pk_mul_f32 v[22:23], v[18:19], v[22:23]
	v_permlane16_swap_b32_e32 v26, v28
	v_add_f32_e32 v0, 1.0, v0
	v_rcp_f32_e32 v20, v0
	v_mul_f32_e32 v0, 0xbfb8aa3b, v19
	v_exp_f32_e32 v0, v0
	s_nop 0
	v_add_f32_e32 v0, 1.0, v0
	v_rcp_f32_e32 v21, v0
	v_mov_b32_e32 v0, v51
	v_pk_fma_f32 v[10:11], v[10:11], v[0:1], v[160:161] op_sel_hi:[1,0,1]
	v_pk_fma_f32 v[14:15], v[14:15], v[0:1], v[164:165] op_sel_hi:[1,0,1]
	v_pk_mul_f32 v[18:19], v[22:23], v[20:21]
	v_pk_mul_f32 v[14:15], v[10:11], v[14:15]
	v_cvt_pk_bf16_f32 v29, v18, v19
	v_add_co_u32_e32 v18, vcc, s0, v138
	s_nop 0
	v_permlane16_swap_b32_e32 v27, v29
	v_addc_co_u32_e32 v19, vcc, 0, v139, vcc
	global_store_dwordx4 v[18:19], v[26:29], off
	v_mul_f32_e32 v18, 0xbfb8aa3b, v10
	v_mul_f32_e32 v10, 0xbfb8aa3b, v11
	v_exp_f32_e32 v18, v18
	v_exp_f32_e32 v10, v10
	v_pk_fma_f32 v[12:13], v[12:13], v[0:1], v[162:163] op_sel_hi:[1,0,1]
	v_pk_fma_f32 v[16:17], v[16:17], v[0:1], v[166:167] op_sel_hi:[1,0,1]
	v_add_f32_e32 v18, 1.0, v18
	v_add_f32_e32 v10, 1.0, v10
	v_rcp_f32_e32 v18, v18
	v_rcp_f32_e32 v19, v10
	v_pk_mul_f32 v[16:17], v[12:13], v[16:17]
	v_pk_fma_f32 v[2:3], v[2:3], v[0:1], v[168:169] op_sel_hi:[1,0,1]
	v_pk_fma_f32 v[6:7], v[6:7], v[0:1], v[172:173] op_sel_hi:[1,0,1]
	v_pk_mul_f32 v[10:11], v[14:15], v[18:19]
	v_pk_mul_f32 v[6:7], v[2:3], v[6:7]
	v_cvt_pk_bf16_f32 v10, v10, v11
	v_mul_f32_e32 v11, 0xbfb8aa3b, v12
	v_exp_f32_e32 v11, v11
	s_nop 0
	v_add_f32_e32 v11, 1.0, v11
	v_rcp_f32_e32 v14, v11
	v_mul_f32_e32 v11, 0xbfb8aa3b, v13
	v_exp_f32_e32 v11, v11
	s_nop 0
	v_add_f32_e32 v11, 1.0, v11
	v_rcp_f32_e32 v15, v11
	s_nop 0
	v_pk_mul_f32 v[12:13], v[16:17], v[14:15]
	s_nop 0
	v_cvt_pk_bf16_f32 v11, v12, v13
	v_mul_f32_e32 v12, 0xbfb8aa3b, v2
	v_mul_f32_e32 v2, 0xbfb8aa3b, v3
	v_exp_f32_e32 v12, v12
	v_exp_f32_e32 v2, v2
	v_add_f32_e32 v12, 1.0, v12
	v_add_f32_e32 v2, 1.0, v2
	v_rcp_f32_e32 v12, v12
	v_rcp_f32_e32 v13, v2
	s_nop 0
	v_pk_mul_f32 v[2:3], v[6:7], v[12:13]
	s_nop 0
	v_cvt_pk_bf16_f32 v12, v2, v3
	v_pk_fma_f32 v[2:3], v[4:5], v[0:1], v[170:171] op_sel_hi:[1,0,1]
	v_pk_fma_f32 v[6:7], v[8:9], v[0:1], v[174:175] op_sel_hi:[1,0,1]
	v_mul_f32_e32 v4, 0xbfb8aa3b, v2
	v_mul_f32_e32 v0, 0xbfb8aa3b, v3
	v_exp_f32_e32 v4, v4
	v_exp_f32_e32 v0, v0
	v_pk_mul_f32 v[6:7], v[2:3], v[6:7]
	v_permlane16_swap_b32_e32 v10, v12
	v_add_f32_e32 v4, 1.0, v4
	v_add_f32_e32 v0, 1.0, v0
	v_rcp_f32_e32 v4, v4
	v_rcp_f32_e32 v5, v0
	s_nop 0
	v_pk_mul_f32 v[2:3], v[6:7], v[4:5]
	s_nop 0
	v_cvt_pk_bf16_f32 v13, v2, v3
	v_add_co_u32_e32 v2, vcc, 0xf2000, v138
	s_nop 0
	v_permlane16_swap_b32_e32 v11, v13
	v_addc_co_u32_e32 v3, vcc, 0, v139, vcc
	global_store_dwordx4 v[2:3], v[10:13], off
	s_waitcnt vmcnt(8)
